# MLA tile loop: K-fragment LDS reads issued one MFMA earlier with counted lgkmcnt(1); 6 horizontal v_pk_add_f32 split to scalar
# speedup vs baseline: 1.0027x; 1.0027x over previous
; #define LAS __attribute__((address_space(3)))
; DI unsigned cvtpk(float lo, float hi) { f32x2_t v = {lo, hi}; bf16x2_t b = __builtin_convertvector(v, bf16x2_t); return __builtin_bit_cast(unsigned, b); }
; DI float fexp2(float x) { return __builtin_amdgcn_exp2f(x); }
; #define MFMA32(a, b, c) __builtin_amdgcn_mfma_f32_32x32x16_bf16((a), (b), (c), 0, 0, 0)
;     ...
;             const float mu = (m == -INFINITY) ? 0.f : m;
;             float rs = 0.f;
; #pragma unroll
;             for (int i = 0; i < 16; i += 2) {
;                 f32x2_t a2 = {s0[i], s0[i + 1]}, b2 = {s1[i], s1[i + 1]}; const f32x2_t nm = {-mu, -mu};
;                 a2 = a2 + nm; b2 = b2 + nm;
;                 s0[i] = fexp2(a2.x); s0[i + 1] = fexp2(a2.y); s1[i] = fexp2(b2.x); s1[i + 1] = fexp2(b2.y);
;                 rs += (s0[i] + s0[i + 1]) + (s1[i] + s1[i + 1]); }
;             l += rs;
;             bf16x8 pb[4];
;             { u32x4 p; p.x = cvtpk(s0[0], s0[1]); p.y = cvtpk(s0[2], s0[3]); p.z = cvtpk(s0[4], s0[5]); p.w = cvtpk(s0[6], s0[7]); pb[0] = __builtin_bit_cast(bf16x8, p);
;               p.x = cvtpk(s0[8], s0[9]); p.y = cvtpk(s0[10], s0[11]); p.z = cvtpk(s0[12], s0[13]); p.w = cvtpk(s0[14], s0[15]); pb[1] = __builtin_bit_cast(bf16x8, p);
;               p.x = cvtpk(s1[0], s1[1]); p.y = cvtpk(s1[2], s1[3]); p.z = cvtpk(s1[4], s1[5]); p.w = cvtpk(s1[6], s1[7]); pb[2] = __builtin_bit_cast(bf16x8, p);
;               p.x = cvtpk(s1[8], s1[9]); p.y = cvtpk(s1[10], s1[11]); p.z = cvtpk(s1[12], s1[13]); p.w = cvtpk(s1[14], s1[15]); pb[3] = __builtin_bit_cast(bf16x8, p); }
;             const LAS unsigned char* vb = bb + KB + n * PV + 8 * h;
; #pragma unroll
;             for (int sx = 0; sx < 4; ++sx) {
;                 const s16x4 a0 = *(const LAS s16x4*)(vb + 32 * sx), a1 = *(const LAS s16x4*)(vb + 32 * sx + 16);
;                 const s16x4 b0 = *(const LAS s16x4*)(vb + 32 * PV + 32 * sx), b1 = *(const LAS s16x4*)(vb + 32 * PV + 32 * sx + 16);
;                 o0 = MFMA32(__builtin_shufflevector(a0, a1, 0, 1, 2, 3, 4, 5, 6, 7), pb[sx], o0);
;                 o1 = MFMA32(__builtin_shufflevector(b0, b1, 0, 1, 2, 3, 4, 5, 6, 7), pb[sx], o1);
;             }
.LBB0_137:
	v_cmp_neq_f32_e32 vcc, s79, v127
	s_nop 1
	v_cndmask_b32_e64 v128, v247, -v127, vcc
	v_add_f32_e32 v66, v66, v128
	v_add_f32_e32 v67, v67, v128
	v_add_f32_e32 v82, v82, v128
	v_add_f32_e32 v83, v83, v128
	v_add_f32_e32 v68, v68, v128
	v_add_f32_e32 v69, v69, v128
	v_add_f32_e32 v84, v84, v128
	v_add_f32_e32 v85, v85, v128
	v_exp_f32_e32 v147, v66
	v_exp_f32_e32 v67, v67
	v_exp_f32_e32 v149, v82
	v_exp_f32_e32 v83, v83
	v_exp_f32_e32 v146, v68
	v_exp_f32_e32 v66, v69
	v_exp_f32_e32 v148, v84
	v_exp_f32_e32 v82, v85
	v_add_f32_e32 v70, v70, v128
	v_add_f32_e32 v71, v71, v128
	v_add_f32_e32 v68, v66, v146
	v_add_f32_e32 v69, v67, v147
	v_exp_f32_e32 v151, v71
	v_add_f32_e32 v84, v82, v148
	v_add_f32_e32 v85, v83, v149
	v_add_f32_e32 v72, v72, v128
	v_add_f32_e32 v73, v73, v128
	v_add_f32_e32 v68, v84, v68
	v_add_f32_e32 v69, v85, v69
	v_add_f32_e32 v84, v86, v128
	v_add_f32_e32 v85, v87, v128
	v_exp_f32_e32 v87, v70
	v_exp_f32_e32 v86, v84
	v_exp_f32_e32 v150, v85
	v_add_f32_e32 v84, v88, v128
	v_add_f32_e32 v85, v89, v128
	v_add_f32_e32 v69, 0, v69
	v_exp_f32_e32 v154, v72
	v_add_f32_e32 v70, v150, v86
	v_add_f32_e32 v71, v151, v87
	v_exp_f32_e32 v155, v73
	v_add_f32_e32 v71, v70, v71
	v_add_f32_e32 v70, v70, v70
	v_exp_f32_e32 v156, v84
	v_exp_f32_e32 v157, v85
	v_add_f32_e32 v72, v74, v128
	v_add_f32_e32 v73, v75, v128
	v_add_f32_e32 v74, v90, v128
	v_add_f32_e32 v75, v91, v128
	v_add_f32_e32 v69, v68, v69
	v_exp_f32_e32 v68, v72
	v_exp_f32_e32 v70, v73
	v_exp_f32_e32 v84, v74
	v_exp_f32_e32 v88, v75
	v_add_f32_e32 v85, v155, v154
	v_add_f32_e32 v89, v157, v156
	v_add_f32_e32 v72, v70, v68
	v_add_f32_e32 v73, v71, v69
	v_add_f32_e32 v74, v88, v84
	v_add_f32_e32 v75, v89, v85
	s_nop 0
	v_add_f32_e32 v72, v74, v72
	v_add_f32_e32 v73, v75, v73
	v_add_f32_e32 v74, v76, v128
	v_add_f32_e32 v75, v77, v128
	v_add_f32_e32 v76, v92, v128
	v_add_f32_e32 v77, v93, v128
	v_exp_f32_e32 v91, v74
	v_exp_f32_e32 v93, v75
	v_exp_f32_e32 v90, v76
	v_exp_f32_e32 v92, v77
	v_add_f32_e32 v76, v94, v128
	v_add_f32_e32 v77, v95, v128
	v_add_f32_e32 v73, v72, v73
	v_add_f32_e32 v72, v72, v72
	v_exp_f32_e32 v85, v76
	v_exp_f32_e32 v89, v77
	v_add_f32_e32 v74, v92, v90
	v_add_f32_e32 v75, v93, v91
	s_nop 0
	v_add_f32_e32 v152, v74, v74
	v_add_f32_e32 v153, v74, v75
	v_add_f32_e32 v74, v78, v128
	v_add_f32_e32 v75, v79, v128
	v_add_f32_e32 v129, v89, v85
	v_exp_f32_e32 v69, v74
	v_exp_f32_e32 v71, v75
	v_add_f32_e32 v74, v80, v128
	v_add_f32_e32 v75, v81, v128
	v_add_f32_e32 v76, v96, v128
	v_add_f32_e32 v77, v97, v128
	v_exp_f32_e32 v72, v74
	v_exp_f32_e32 v152, v75
	v_exp_f32_e32 v94, v76
	v_exp_f32_e32 v128, v77
	v_add_f32_e32 v95, v71, v69
	v_add_f32_e32 v74, v152, v72
	v_add_f32_e32 v75, v153, v73
	v_cvt_pk_bf16_f32 v79, v146, v66
	v_add_f32_e32 v76, v128, v94
	v_add_f32_e32 v77, v129, v95
	v_cvt_pk_bf16_f32 v66, v84, v88
	v_add_f32_e32 v74, v76, v74
	v_add_f32_e32 v75, v77, v75
	v_cvt_pk_bf16_f32 v77, v72, v152
	v_cvt_pk_bf16_f32 v72, v86, v150
	v_add3_u32 v86, s38, v188, v164
	v_cvt_pk_bf16_f32 v76, v69, v71
	v_cvt_pk_bf16_f32 v69, v94, v128
	v_add_u32_e32 v94, 0x3000, v86
	v_add_f32_e32 v73, v74, v75
	v_cvt_pk_bf16_f32 v74, v68, v70
	v_cvt_pk_bf16_f32 v70, v149, v83
	v_cvt_pk_bf16_f32 v71, v148, v82
	v_cvt_pk_bf16_f32 v68, v85, v89
	ds_read2_b64 v[82:85], v94 offset0:160 offset1:162
	v_add_u32_e32 v95, 0x2000, v86
	v_cvt_pk_bf16_f32 v78, v147, v67
	v_cvt_pk_bf16_f32 v80, v87, v151
	v_cvt_pk_bf16_f32 v75, v91, v93
	v_cvt_pk_bf16_f32 v67, v90, v92
	ds_read2_b64 v[86:89], v95 offset0:128 offset1:130
	ds_read2_b64 v[90:93], v95 offset0:132 offset1:134
	v_cvt_pk_bf16_f32 v81, v154, v155
	v_add_f32_e32 v201, v201, v73
	v_cvt_pk_bf16_f32 v73, v156, v157
	s_waitcnt lgkmcnt(1)
	v_mfma_f32_32x32x16_bf16 v[34:49], v[86:89], v[78:81], v[34:49]
	v_mfma_f32_32x32x16_bf16 v[50:65], v[82:85], v[78:81], v[50:65]
	ds_read2_b64 v[78:81], v94 offset0:164 offset1:166
	s_waitcnt lgkmcnt(1)
	v_mfma_f32_32x32x16_bf16 v[34:49], v[90:93], v[74:77], v[34:49]
	s_waitcnt lgkmcnt(0)
	v_mfma_f32_32x32x16_bf16 v[50:65], v[78:81], v[74:77], v[50:65]
	ds_read2_b64 v[74:77], v95 offset0:136 offset1:138
	ds_read2_b64 v[78:81], v94 offset0:168 offset1:170
	s_waitcnt lgkmcnt(1)
	v_mfma_f32_32x32x16_bf16 v[34:49], v[74:77], v[70:73], v[34:49]
	s_waitcnt lgkmcnt(0)
	v_mfma_f32_32x32x16_bf16 v[50:65], v[78:81], v[70:73], v[50:65]
	ds_read2_b64 v[70:73], v95 offset0:140 offset1:142
	ds_read2_b64 v[74:77], v94 offset0:172 offset1:174
	s_waitcnt lgkmcnt(1)
	v_mfma_f32_32x32x16_bf16 v[34:49], v[70:73], v[66:69], v[34:49]
	s_waitcnt lgkmcnt(0)
	v_mfma_f32_32x32x16_bf16 v[50:65], v[74:77], v[66:69], v[50:65]

; #define LAS __attribute__((address_space(3)))
; DI unsigned cvtpk(float lo, float hi) { f32x2_t v = {lo, hi}; bf16x2_t b = __builtin_convertvector(v, bf16x2_t); return __builtin_bit_cast(unsigned, b); }
; DI float fexp2(float x) { return __builtin_amdgcn_exp2f(x); }
; #define MFMA32(a, b, c) __builtin_amdgcn_mfma_f32_32x32x16_bf16((a), (b), (c), 0, 0, 0)
;     ...
;             const float mu = (m == -INFINITY) ? 0.f : m;
;             float rs = 0.f;
; #pragma unroll
;             for (int i = 0; i < 16; i += 2) {
;                 f32x2_t a2 = {s0[i], s0[i + 1]}, b2 = {s1[i], s1[i + 1]}; const f32x2_t nm = {-mu, -mu};
;                 a2 = a2 + nm; b2 = b2 + nm;
;                 s0[i] = fexp2(a2.x); s0[i + 1] = fexp2(a2.y); s1[i] = fexp2(b2.x); s1[i + 1] = fexp2(b2.y);
;                 rs += (s0[i] + s0[i + 1]) + (s1[i] + s1[i + 1]); }
;             l += rs;
;             bf16x8 pb[4];
;             { u32x4 p; p.x = cvtpk(s0[0], s0[1]); p.y = cvtpk(s0[2], s0[3]); p.z = cvtpk(s0[4], s0[5]); p.w = cvtpk(s0[6], s0[7]); pb[0] = __builtin_bit_cast(bf16x8, p);
;               p.x = cvtpk(s0[8], s0[9]); p.y = cvtpk(s0[10], s0[11]); p.z = cvtpk(s0[12], s0[13]); p.w = cvtpk(s0[14], s0[15]); pb[1] = __builtin_bit_cast(bf16x8, p);
;               p.x = cvtpk(s1[0], s1[1]); p.y = cvtpk(s1[2], s1[3]); p.z = cvtpk(s1[4], s1[5]); p.w = cvtpk(s1[6], s1[7]); pb[2] = __builtin_bit_cast(bf16x8, p);
;               p.x = cvtpk(s1[8], s1[9]); p.y = cvtpk(s1[10], s1[11]); p.z = cvtpk(s1[12], s1[13]); p.w = cvtpk(s1[14], s1[15]); pb[3] = __builtin_bit_cast(bf16x8, p); }
;             const LAS unsigned char* vb = bb + KB + n * PV + 8 * h;
; #pragma unroll
;             for (int sx = 0; sx < 4; ++sx) {
;                 const s16x4 a0 = *(const LAS s16x4*)(vb + 32 * sx), a1 = *(const LAS s16x4*)(vb + 32 * sx + 16);
;                 const s16x4 b0 = *(const LAS s16x4*)(vb + 32 * PV + 32 * sx), b1 = *(const LAS s16x4*)(vb + 32 * PV + 32 * sx + 16);
;                 o0 = MFMA32(__builtin_shufflevector(a0, a1, 0, 1, 2, 3, 4, 5, 6, 7), pb[sx], o0);
;                 o1 = MFMA32(__builtin_shufflevector(b0, b1, 0, 1, 2, 3, 4, 5, 6, 7), pb[sx], o1);
;             }
.LBB0_155:
	v_cmp_neq_f32_e32 vcc, s79, v213
	s_nop 1
	v_cndmask_b32_e64 v202, v247, -v213, vcc
	v_add_f32_e32 v98, v98, v202
	v_add_f32_e32 v99, v99, v202
	v_add_f32_e32 v114, v114, v202
	v_add_f32_e32 v115, v115, v202
	v_add_f32_e32 v100, v100, v202
	v_add_f32_e32 v101, v101, v202
	v_add_f32_e32 v116, v116, v202
	v_add_f32_e32 v117, v117, v202
	v_exp_f32_e32 v205, v98
	v_exp_f32_e32 v99, v99
	v_exp_f32_e32 v215, v114
	v_exp_f32_e32 v115, v115
	v_exp_f32_e32 v204, v100
	v_exp_f32_e32 v98, v101
	v_exp_f32_e32 v214, v116
	v_exp_f32_e32 v114, v117
	v_add_f32_e32 v102, v102, v202
	v_add_f32_e32 v103, v103, v202
	v_add_f32_e32 v100, v98, v204
	v_add_f32_e32 v101, v99, v205
	v_exp_f32_e32 v217, v103
	v_add_f32_e32 v116, v114, v214
	v_add_f32_e32 v117, v115, v215
	v_add_f32_e32 v104, v104, v202
	v_add_f32_e32 v105, v105, v202
	v_add_f32_e32 v100, v116, v100
	v_add_f32_e32 v101, v117, v101
	v_add_f32_e32 v116, v118, v202
	v_add_f32_e32 v117, v119, v202
	v_exp_f32_e32 v119, v102
	v_exp_f32_e32 v118, v116
	v_exp_f32_e32 v216, v117
	v_add_f32_e32 v116, v120, v202
	v_add_f32_e32 v117, v121, v202
	v_add_f32_e32 v101, 0, v101
	v_exp_f32_e32 v220, v104
	v_add_f32_e32 v102, v216, v118
	v_add_f32_e32 v103, v217, v119
	v_exp_f32_e32 v221, v105
	v_add_f32_e32 v103, v102, v103
	v_add_f32_e32 v102, v102, v102
	v_exp_f32_e32 v222, v116
	v_exp_f32_e32 v223, v117
	v_add_f32_e32 v104, v106, v202
	v_add_f32_e32 v105, v107, v202
	v_add_f32_e32 v106, v122, v202
	v_add_f32_e32 v107, v123, v202
	v_add_f32_e32 v101, v100, v101
	v_exp_f32_e32 v100, v104
	v_exp_f32_e32 v102, v105
	v_exp_f32_e32 v116, v106
	v_exp_f32_e32 v120, v107
	v_add_f32_e32 v117, v221, v220
	v_add_f32_e32 v121, v223, v222
	v_add_f32_e32 v104, v102, v100
	v_add_f32_e32 v105, v103, v101
	v_add_f32_e32 v106, v120, v116
	v_add_f32_e32 v107, v121, v117
	s_nop 0
	v_add_f32_e32 v104, v106, v104
	v_add_f32_e32 v105, v107, v105
	v_add_f32_e32 v106, v108, v202
	v_add_f32_e32 v107, v109, v202
	v_add_f32_e32 v108, v124, v202
	v_add_f32_e32 v109, v125, v202
	v_exp_f32_e32 v123, v106
	v_exp_f32_e32 v125, v107
	v_exp_f32_e32 v122, v108
	v_exp_f32_e32 v124, v109
	v_add_f32_e32 v108, v126, v202
	v_add_f32_e32 v109, v127, v202
	v_add_f32_e32 v105, v104, v105
	v_add_f32_e32 v104, v104, v104
	v_exp_f32_e32 v117, v108
	v_exp_f32_e32 v121, v109
	v_add_f32_e32 v106, v124, v122
	v_add_f32_e32 v107, v125, v123
	s_nop 0
	v_pk_add_f32 v[218:219], v[106:107], v[106:107] op_sel_hi:[0,1]
	v_add_f32_e32 v106, v110, v202
	v_add_f32_e32 v107, v111, v202
	v_add_f32_e32 v203, v121, v117
	v_exp_f32_e32 v101, v106
	v_exp_f32_e32 v103, v107
	v_add_f32_e32 v106, v112, v202
	v_add_f32_e32 v107, v113, v202
	v_add_f32_e32 v108, v128, v202
	v_add_f32_e32 v109, v129, v202
	v_exp_f32_e32 v104, v106
	v_exp_f32_e32 v218, v107
	v_exp_f32_e32 v126, v108
	v_exp_f32_e32 v202, v109
	v_add_f32_e32 v127, v103, v101
	v_add_f32_e32 v106, v218, v104
	v_add_f32_e32 v107, v219, v105
	v_cvt_pk_bf16_f32 v111, v204, v98
	v_add_f32_e32 v108, v202, v126
	v_add_f32_e32 v109, v203, v127
	v_cvt_pk_bf16_f32 v98, v116, v120
	v_add_f32_e32 v106, v108, v106
	v_add_f32_e32 v107, v109, v107
	v_cvt_pk_bf16_f32 v109, v104, v218
	v_cvt_pk_bf16_f32 v104, v118, v216
	v_add3_u32 v118, s9, v188, v164
	v_cvt_pk_bf16_f32 v108, v101, v103
	v_cvt_pk_bf16_f32 v101, v126, v202
	v_add_u32_e32 v126, 0x3000, v118
	v_add_f32_e32 v105, v106, v107
	v_cvt_pk_bf16_f32 v106, v100, v102
	v_cvt_pk_bf16_f32 v102, v215, v115
	v_cvt_pk_bf16_f32 v103, v214, v114
	v_cvt_pk_bf16_f32 v100, v117, v121
	ds_read2_b64 v[114:117], v126 offset0:160 offset1:162
	v_add_u32_e32 v127, 0x2000, v118
	v_cvt_pk_bf16_f32 v110, v205, v99
	v_cvt_pk_bf16_f32 v112, v119, v217
	v_cvt_pk_bf16_f32 v107, v123, v125
	v_cvt_pk_bf16_f32 v99, v122, v124
	ds_read2_b64 v[118:121], v127 offset0:128 offset1:130
	ds_read2_b64 v[122:125], v127 offset0:132 offset1:134
	v_cvt_pk_bf16_f32 v113, v220, v221
	v_add_f32_e32 v211, v211, v105
	v_cvt_pk_bf16_f32 v105, v222, v223
	s_waitcnt lgkmcnt(1)
	v_mfma_f32_32x32x16_bf16 v[66:81], v[118:121], v[110:113], v[66:81]
	v_mfma_f32_32x32x16_bf16 v[82:97], v[114:117], v[110:113], v[82:97]
	ds_read2_b64 v[110:113], v126 offset0:164 offset1:166
	s_waitcnt lgkmcnt(1)
	v_mfma_f32_32x32x16_bf16 v[66:81], v[122:125], v[106:109], v[66:81]
	s_waitcnt lgkmcnt(0)
	v_mfma_f32_32x32x16_bf16 v[82:97], v[110:113], v[106:109], v[82:97]
	ds_read2_b64 v[106:109], v127 offset0:136 offset1:138
	ds_read2_b64 v[110:113], v126 offset0:168 offset1:170
	s_waitcnt lgkmcnt(1)
	v_mfma_f32_32x32x16_bf16 v[66:81], v[106:109], v[102:105], v[66:81]
	s_waitcnt lgkmcnt(0)
	v_mfma_f32_32x32x16_bf16 v[82:97], v[110:113], v[102:105], v[82:97]
	ds_read2_b64 v[102:105], v127 offset0:140 offset1:142
	ds_read2_b64 v[106:109], v126 offset0:172 offset1:174
	s_waitcnt lgkmcnt(1)
	v_mfma_f32_32x32x16_bf16 v[66:81], v[102:105], v[98:101], v[66:81]
	s_waitcnt lgkmcnt(0)
	v_mfma_f32_32x32x16_bf16 v[82:97], v[106:109], v[98:101], v[82:97]
	s_cmp_ge_i32 s24, s58
	s_mov_b64 s[10:11], -1
	s_cbranch_scc0 .LBB0_158

; #define LAS __attribute__((address_space(3)))
; DI unsigned cvtpk(float lo, float hi) { f32x2_t v = {lo, hi}; bf16x2_t b = __builtin_convertvector(v, bf16x2_t); return __builtin_bit_cast(unsigned, b); }
; DI float fexp2(float x) { return __builtin_amdgcn_exp2f(x); }
; #define MFMA32(a, b, c) __builtin_amdgcn_mfma_f32_32x32x16_bf16((a), (b), (c), 0, 0, 0)
;     ...
;             const float mu = (m == -INFINITY) ? 0.f : m;
;             float rs = 0.f;
; #pragma unroll
;             for (int i = 0; i < 16; i += 2) {
;                 f32x2_t a2 = {s0[i], s0[i + 1]}, b2 = {s1[i], s1[i + 1]}; const f32x2_t nm = {-mu, -mu};
;                 a2 = a2 + nm; b2 = b2 + nm;
;                 s0[i] = fexp2(a2.x); s0[i + 1] = fexp2(a2.y); s1[i] = fexp2(b2.x); s1[i + 1] = fexp2(b2.y);
;                 rs += (s0[i] + s0[i + 1]) + (s1[i] + s1[i + 1]); }
;             l += rs;
;             bf16x8 pb[4];
;             { u32x4 p; p.x = cvtpk(s0[0], s0[1]); p.y = cvtpk(s0[2], s0[3]); p.z = cvtpk(s0[4], s0[5]); p.w = cvtpk(s0[6], s0[7]); pb[0] = __builtin_bit_cast(bf16x8, p);
;               p.x = cvtpk(s0[8], s0[9]); p.y = cvtpk(s0[10], s0[11]); p.z = cvtpk(s0[12], s0[13]); p.w = cvtpk(s0[14], s0[15]); pb[1] = __builtin_bit_cast(bf16x8, p);
;               p.x = cvtpk(s1[0], s1[1]); p.y = cvtpk(s1[2], s1[3]); p.z = cvtpk(s1[4], s1[5]); p.w = cvtpk(s1[6], s1[7]); pb[2] = __builtin_bit_cast(bf16x8, p);
;               p.x = cvtpk(s1[8], s1[9]); p.y = cvtpk(s1[10], s1[11]); p.z = cvtpk(s1[12], s1[13]); p.w = cvtpk(s1[14], s1[15]); pb[3] = __builtin_bit_cast(bf16x8, p); }
;             const LAS unsigned char* vb = bb + KB + n * PV + 8 * h;
; #pragma unroll
;             for (int sx = 0; sx < 4; ++sx) {
;                 const s16x4 a0 = *(const LAS s16x4*)(vb + 32 * sx), a1 = *(const LAS s16x4*)(vb + 32 * sx + 16);
;                 const s16x4 b0 = *(const LAS s16x4*)(vb + 32 * PV + 32 * sx), b1 = *(const LAS s16x4*)(vb + 32 * PV + 32 * sx + 16);
;                 o0 = MFMA32(__builtin_shufflevector(a0, a1, 0, 1, 2, 3, 4, 5, 6, 7), pb[sx], o0);
;                 o1 = MFMA32(__builtin_shufflevector(b0, b1, 0, 1, 2, 3, 4, 5, 6, 7), pb[sx], o1);
;             }
.LBB0_196:
	v_cmp_neq_f32_e32 vcc, s79, v115
	s_nop 1
	v_cndmask_b32_e64 v116, v247, -v115, vcc
	v_add_f32_e32 v34, v34, v116
	v_add_f32_e32 v35, v35, v116
	v_add_f32_e32 v50, v50, v116
	v_add_f32_e32 v51, v51, v116
	v_add_f32_e32 v36, v36, v116
	v_add_f32_e32 v37, v37, v116
	v_add_f32_e32 v52, v52, v116
	v_add_f32_e32 v53, v53, v116
	v_exp_f32_e32 v119, v34
	v_exp_f32_e32 v35, v35
	v_exp_f32_e32 v121, v50
	v_exp_f32_e32 v51, v51
	v_exp_f32_e32 v118, v36
	v_exp_f32_e32 v34, v37
	v_exp_f32_e32 v120, v52
	v_exp_f32_e32 v50, v53
	v_add_f32_e32 v38, v38, v116
	v_add_f32_e32 v39, v39, v116
	v_add_f32_e32 v36, v34, v118
	v_add_f32_e32 v37, v35, v119
	v_exp_f32_e32 v123, v39
	v_add_f32_e32 v52, v50, v120
	v_add_f32_e32 v53, v51, v121
	v_add_f32_e32 v40, v40, v116
	v_add_f32_e32 v41, v41, v116
	v_add_f32_e32 v36, v52, v36
	v_add_f32_e32 v37, v53, v37
	v_add_f32_e32 v52, v54, v116
	v_add_f32_e32 v53, v55, v116
	v_exp_f32_e32 v55, v38
	v_exp_f32_e32 v54, v52
	v_exp_f32_e32 v122, v53
	v_add_f32_e32 v52, v56, v116
	v_add_f32_e32 v53, v57, v116
	v_add_f32_e32 v37, 0, v37
	v_exp_f32_e32 v126, v40
	v_add_f32_e32 v38, v122, v54
	v_add_f32_e32 v39, v123, v55
	v_exp_f32_e32 v127, v41
	v_add_f32_e32 v39, v38, v39
	v_add_f32_e32 v38, v38, v38
	v_exp_f32_e32 v128, v52
	v_exp_f32_e32 v129, v53
	v_add_f32_e32 v40, v42, v116
	v_add_f32_e32 v41, v43, v116
	v_add_f32_e32 v42, v58, v116
	v_add_f32_e32 v43, v59, v116
	v_add_f32_e32 v37, v36, v37
	v_exp_f32_e32 v36, v40
	v_exp_f32_e32 v38, v41
	v_exp_f32_e32 v52, v42
	v_exp_f32_e32 v56, v43
	v_add_f32_e32 v53, v127, v126
	v_add_f32_e32 v57, v129, v128
	v_add_f32_e32 v40, v38, v36
	v_add_f32_e32 v41, v39, v37
	v_add_f32_e32 v42, v56, v52
	v_add_f32_e32 v43, v57, v53
	s_nop 0
	v_add_f32_e32 v40, v42, v40
	v_add_f32_e32 v41, v43, v41
	v_add_f32_e32 v42, v44, v116
	v_add_f32_e32 v43, v45, v116
	v_add_f32_e32 v44, v60, v116
	v_add_f32_e32 v45, v61, v116
	v_exp_f32_e32 v59, v42
	v_exp_f32_e32 v61, v43
	v_exp_f32_e32 v58, v44
	v_exp_f32_e32 v60, v45
	v_add_f32_e32 v44, v62, v116
	v_add_f32_e32 v45, v63, v116
	v_pk_add_f32 v[40:41], v[40:41], v[40:41] op_sel_hi:[0,1]
	v_exp_f32_e32 v53, v44
	v_exp_f32_e32 v57, v45
	v_add_f32_e32 v42, v60, v58
	v_add_f32_e32 v43, v61, v59
	s_nop 0
	v_pk_add_f32 v[124:125], v[42:43], v[42:43] op_sel_hi:[0,1]
	v_add_f32_e32 v42, v46, v116
	v_add_f32_e32 v43, v47, v116
	v_add_f32_e32 v117, v57, v53
	v_exp_f32_e32 v37, v42
	v_exp_f32_e32 v39, v43
	v_add_f32_e32 v42, v48, v116
	v_add_f32_e32 v43, v49, v116
	v_add_f32_e32 v44, v64, v116
	v_add_f32_e32 v45, v65, v116
	v_exp_f32_e32 v40, v42
	v_exp_f32_e32 v124, v43
	v_exp_f32_e32 v62, v44
	v_exp_f32_e32 v116, v45
	v_add_f32_e32 v63, v39, v37
	v_add_f32_e32 v42, v124, v40
	v_add_f32_e32 v43, v125, v41
	v_cvt_pk_bf16_f32 v47, v118, v34
	v_add_f32_e32 v44, v116, v62
	v_add_f32_e32 v45, v117, v63
	v_cvt_pk_bf16_f32 v34, v52, v56
	v_add_f32_e32 v42, v44, v42
	v_add_f32_e32 v43, v45, v43
	v_cvt_pk_bf16_f32 v45, v40, v124
	v_cvt_pk_bf16_f32 v40, v54, v122
	v_add3_u32 v54, s4, v188, v164
	v_cvt_pk_bf16_f32 v44, v37, v39
	v_cvt_pk_bf16_f32 v37, v62, v116
	v_add_u32_e32 v62, 0x3000, v54
	v_add_f32_e32 v41, v42, v43
	v_cvt_pk_bf16_f32 v42, v36, v38
	v_cvt_pk_bf16_f32 v38, v121, v51
	v_cvt_pk_bf16_f32 v39, v120, v50
	v_cvt_pk_bf16_f32 v36, v53, v57
	ds_read2_b64 v[50:53], v62 offset0:160 offset1:162
	v_add_u32_e32 v63, 0x2000, v54
	v_cvt_pk_bf16_f32 v46, v119, v35
	v_cvt_pk_bf16_f32 v48, v55, v123
	v_cvt_pk_bf16_f32 v43, v59, v61
	v_cvt_pk_bf16_f32 v35, v58, v60
	ds_read2_b64 v[54:57], v63 offset0:128 offset1:130
	ds_read2_b64 v[58:61], v63 offset0:132 offset1:134
	v_cvt_pk_bf16_f32 v49, v126, v127
	v_add_f32_e32 v113, v113, v41
	v_cvt_pk_bf16_f32 v41, v128, v129
	ds_read2_b64 v[116:119], v62 offset0:164 offset1:166
	ds_read2_b64 v[120:123], v63 offset0:136 offset1:138
	s_waitcnt lgkmcnt(3)
	v_mfma_f32_32x32x16_bf16 v[18:33], v[54:57], v[46:49], v[18:33]
	v_mfma_f32_32x32x16_bf16 v[2:17], v[50:53], v[46:49], v[2:17]
	ds_read2_b64 v[54:57], v62 offset0:168 offset1:170
	ds_read2_b64 v[50:53], v63 offset0:140 offset1:142
	s_waitcnt lgkmcnt(4)
	v_mfma_f32_32x32x16_bf16 v[18:33], v[58:61], v[42:45], v[18:33]
	ds_read2_b64 v[58:61], v62 offset0:172 offset1:174
	s_waitcnt lgkmcnt(4)
	v_mfma_f32_32x32x16_bf16 v[2:17], v[116:119], v[42:45], v[2:17]
	s_waitcnt lgkmcnt(3)
	v_mfma_f32_32x32x16_bf16 v[18:33], v[120:123], v[38:41], v[18:33]
	s_waitcnt lgkmcnt(2)
	v_mfma_f32_32x32x16_bf16 v[2:17], v[54:57], v[38:41], v[2:17]
	s_waitcnt lgkmcnt(1)
	v_mfma_f32_32x32x16_bf16 v[18:33], v[50:53], v[34:37], v[18:33]
	s_waitcnt lgkmcnt(0)
	v_mfma_f32_32x32x16_bf16 v[2:17], v[58:61], v[34:37], v[2:17]
	s_cmp_ge_i32 s8, s14
	s_mov_b64 s[4:5], -1
	s_cbranch_scc0 .LBB0_190

; #define LAS __attribute__((address_space(3)))
; #define MFMA32(a, b, c) __builtin_amdgcn_mfma_f32_32x32x16_bf16((a), (b), (c), 0, 0, 0)
;     ...
;             const LAS unsigned char* bb = tbuf + (kt & 1) * BUF;
;             const int k0 = 64 * kt;
;             const int dbase = tq - k0 - 4 * h;
;             const LAS float* tb = tab - dbase * DSC;
;             f32x16 s0, s1;
;             if (BIAS) {
; #pragma unroll
;                 for (int i = 0; i < 16; ++i) { const int c = (i & 3) + 8 * (i >> 2); s0[i] = tb[c * DSC]; s1[i] = tb[(c + 32) * DSC]; }
;             } else {
; #pragma unroll
;                 for (int i = 0; i < 16; ++i) { s0[i] = 0.f; s1[i] = 0.f; }
;             }
; #pragma unroll
;             for (int ks = 0; ks < DK / 16; ++ks) { const bf16x8 ka = *(const LAS bf16x8*)(bb + n * PK + (16 * ks + 8 * h) * 2), kb2 = *(const LAS bf16x8*)(bb + (32 + n) * PK + (16 * ks + 8 * h) * 2);
;                 s0 = MFMA32(ka, qf[ks], s0); s1 = MFMA32(kb2, qf[ks], s1); }
;             const bool interior = (tq_min >= k0 + 63) && (tq_max - k0 < W) && (!SEL || __builtin_amdgcn_ballot_w64(!selok) == 0ull);
;             if (!interior) {
; #pragma unroll
;                 for (int i = 0; i < 16; ++i) { const int c = (i & 3) + 8 * (i >> 2);
;                     s0[i] = ((unsigned)(dbase - c) < (unsigned)W && selok) ? s0[i] : -INFINITY;
;                     s1[i] = ((unsigned)(dbase - c - 32) < (unsigned)W && selok) ? s1[i] : -INFINITY; }
;             }
.LBB0_249:
	s_bitcmp1_b32 s45, 0
	s_cselect_b32 s10, 0x5600, 0
	s_add_i32 s10, s10, 0
	v_add3_u32 v154, s10, v115, v118
	ds_read_b128 v[34:37], v154 offset:10752
	ds_read_b128 v[38:41], v154 offset:4096
	ds_read_b128 v[146:149], v154 offset:4128
	ds_read_b128 v[150:153], v154 offset:10784
	s_add_i32 s11, s48, 0xffffffbf
	s_cmp_ge_i32 s38, s11
	s_waitcnt lgkmcnt(2)
	v_mfma_f32_32x32x16_bf16 v[50:65], v[38:41], v[66:69], 0
	s_cselect_b64 s[26:27], -1, 0
	s_cmp_lt_i32 s42, 2.0
	s_cselect_b64 s[52:53], -1, 0
	s_and_b64 s[26:27], s[26:27], s[52:53]
	s_and_b64 vcc, exec, s[26:27]
	v_mfma_f32_32x32x16_bf16 v[34:49], v[34:37], v[66:69], 0
	s_waitcnt lgkmcnt(1)
	v_mfma_f32_32x32x16_bf16 v[50:65], v[146:149], v[70:73], v[50:65]
	ds_read_b128 v[146:149], v154 offset:4160
	s_waitcnt lgkmcnt(1)
	v_mfma_f32_32x32x16_bf16 v[34:49], v[150:153], v[70:73], v[34:49]
	ds_read_b128 v[150:153], v154 offset:10816
	s_waitcnt lgkmcnt(1)
	v_mfma_f32_32x32x16_bf16 v[50:65], v[146:149], v[74:77], v[50:65]
	ds_read_b128 v[146:149], v154 offset:4192
	s_waitcnt lgkmcnt(1)
	v_mfma_f32_32x32x16_bf16 v[34:49], v[150:153], v[74:77], v[34:49]
	ds_read_b128 v[150:153], v154 offset:10848
	s_waitcnt lgkmcnt(1)
	v_mfma_f32_32x32x16_bf16 v[50:65], v[146:149], v[78:81], v[50:65]
	ds_read_b128 v[146:149], v154 offset:4224
	s_waitcnt lgkmcnt(1)
	v_mfma_f32_32x32x16_bf16 v[34:49], v[150:153], v[78:81], v[34:49]
	ds_read_b128 v[150:153], v154 offset:10880
	s_waitcnt lgkmcnt(1)
	v_mfma_f32_32x32x16_bf16 v[50:65], v[146:149], v[82:85], v[50:65]
	ds_read_b128 v[146:149], v154 offset:4256
	s_waitcnt lgkmcnt(1)
	v_mfma_f32_32x32x16_bf16 v[34:49], v[150:153], v[82:85], v[34:49]
	ds_read_b128 v[150:153], v154 offset:10912
	s_waitcnt lgkmcnt(1)
	v_mfma_f32_32x32x16_bf16 v[50:65], v[146:149], v[86:89], v[50:65]
	s_waitcnt lgkmcnt(0)
	v_mfma_f32_32x32x16_bf16 v[34:49], v[150:153], v[86:89], v[34:49]
	s_cbranch_vccnz .LBB0_251
	v_add_u32_e32 v146, s42, v121
	v_subrev_u32_e32 v147, 31, v146
	v_cmp_gt_u32_e32 vcc, 2.0, v147
	v_subrev_u32_e32 v147, 63, v146
	s_nop 4
	v_cndmask_b32_e32 v50, v246, v50, vcc
	v_cmp_gt_u32_e32 vcc, 2.0, v147
	v_subrev_u32_e32 v147, 32, v146
	s_nop 0
	v_cndmask_b32_e32 v34, v246, v34, vcc
	v_cmp_gt_u32_e32 vcc, 2.0, v147
	v_subrev_u32_e32 v147, 64, v146
	s_nop 0
	v_cndmask_b32_e32 v51, v246, v51, vcc
	v_cmp_gt_u32_e32 vcc, 2.0, v147
	v_subrev_u32_e32 v147, 33, v146
	s_nop 0
	v_cndmask_b32_e32 v35, v246, v35, vcc
	v_cmp_gt_u32_e32 vcc, 2.0, v147
	v_add_u32_e32 v147, 0xffffffbf, v146
	s_nop 0
	v_cndmask_b32_e32 v52, v246, v52, vcc
	v_cmp_gt_u32_e32 vcc, 2.0, v147
	v_subrev_u32_e32 v147, 34, v146
	s_nop 0
	v_cndmask_b32_e32 v36, v246, v36, vcc
	v_cmp_gt_u32_e32 vcc, 2.0, v147
	v_add_u32_e32 v147, 0xffffffbe, v146
	s_nop 0
	v_cndmask_b32_e32 v53, v246, v53, vcc
	v_cmp_gt_u32_e32 vcc, 2.0, v147
	v_subrev_u32_e32 v147, 39, v146
	s_nop 0
	v_cndmask_b32_e32 v37, v246, v37, vcc
	v_cmp_gt_u32_e32 vcc, 2.0, v147
	v_add_u32_e32 v147, 0xffffffb9, v146
	s_nop 0
	v_cndmask_b32_e32 v54, v246, v54, vcc
	v_cmp_gt_u32_e32 vcc, 2.0, v147
	v_subrev_u32_e32 v147, 40, v146
	s_nop 0
	v_cndmask_b32_e32 v38, v246, v38, vcc
	v_cmp_gt_u32_e32 vcc, 2.0, v147
	v_add_u32_e32 v147, 0xffffffb8, v146
	s_nop 0
	v_cndmask_b32_e32 v55, v246, v55, vcc
	v_cmp_gt_u32_e32 vcc, 2.0, v147
	v_subrev_u32_e32 v147, 41, v146
	s_nop 0
	v_cndmask_b32_e32 v39, v246, v39, vcc
	v_cmp_gt_u32_e32 vcc, 2.0, v147
	v_add_u32_e32 v147, 0xffffffb7, v146
	s_nop 0
	v_cndmask_b32_e32 v56, v246, v56, vcc
	v_cmp_gt_u32_e32 vcc, 2.0, v147
	v_subrev_u32_e32 v147, 42, v146
	s_nop 0
	v_cndmask_b32_e32 v40, v246, v40, vcc
	v_cmp_gt_u32_e32 vcc, 2.0, v147
	v_add_u32_e32 v147, 0xffffffb6, v146
	s_nop 0
	v_cndmask_b32_e32 v57, v246, v57, vcc
	v_cmp_gt_u32_e32 vcc, 2.0, v147
	v_subrev_u32_e32 v147, 47, v146
	s_nop 0
	v_cndmask_b32_e32 v41, v246, v41, vcc
	v_cmp_gt_u32_e32 vcc, 2.0, v147
	v_add_u32_e32 v147, 0xffffffb1, v146
	s_nop 0
	v_cndmask_b32_e32 v58, v246, v58, vcc
	v_cmp_gt_u32_e32 vcc, 2.0, v147
	v_subrev_u32_e32 v147, 48, v146
	s_nop 0
	v_cndmask_b32_e32 v42, v246, v42, vcc
	v_cmp_gt_u32_e32 vcc, 2.0, v147
	v_add_u32_e32 v147, 0xffffffb0, v146
	s_nop 0
	v_cndmask_b32_e32 v59, v246, v59, vcc
	v_cmp_gt_u32_e32 vcc, 2.0, v147
	v_subrev_u32_e32 v147, 49, v146
	s_nop 0
	v_cndmask_b32_e32 v43, v246, v43, vcc
	v_cmp_gt_u32_e32 vcc, 2.0, v147
	v_add_u32_e32 v147, 0xffffffaf, v146
	s_nop 0
	v_cndmask_b32_e32 v60, v246, v60, vcc
	v_cmp_gt_u32_e32 vcc, 2.0, v147
	v_subrev_u32_e32 v147, 50, v146
	s_nop 0
	v_cndmask_b32_e32 v44, v246, v44, vcc
	v_cmp_gt_u32_e32 vcc, 2.0, v147
	v_add_u32_e32 v147, 0xffffffae, v146
	s_nop 0
	v_cndmask_b32_e32 v61, v246, v61, vcc
	v_cmp_gt_u32_e32 vcc, 2.0, v147
	v_subrev_u32_e32 v147, 55, v146
	s_nop 0
	v_cndmask_b32_e32 v45, v246, v45, vcc
	v_cmp_gt_u32_e32 vcc, 2.0, v147
	v_add_u32_e32 v147, 0xffffffa9, v146
	s_nop 0
	v_cndmask_b32_e32 v62, v246, v62, vcc
	v_cmp_gt_u32_e32 vcc, 2.0, v147
	v_subrev_u32_e32 v147, 56, v146
	s_nop 0
	v_cndmask_b32_e32 v46, v246, v46, vcc
	v_cmp_gt_u32_e32 vcc, 2.0, v147
	v_add_u32_e32 v147, 0xffffffa8, v146
	s_nop 0
	v_cndmask_b32_e32 v63, v246, v63, vcc
	v_cmp_gt_u32_e32 vcc, 2.0, v147
	v_subrev_u32_e32 v147, 57, v146
	s_nop 0
	v_cndmask_b32_e32 v47, v246, v47, vcc
	v_cmp_gt_u32_e32 vcc, 2.0, v147
	v_add_u32_e32 v147, 0xffffffa7, v146
	s_nop 0
	v_cndmask_b32_e32 v64, v246, v64, vcc
	v_cmp_gt_u32_e32 vcc, 2.0, v147
	v_subrev_u32_e32 v147, 58, v146
	v_add_u32_e32 v146, 0xffffffa6, v146
	v_cndmask_b32_e32 v48, v246, v48, vcc
	v_cmp_gt_u32_e32 vcc, 2.0, v147
	s_nop 1
	v_cndmask_b32_e32 v65, v246, v65, vcc
	v_cmp_gt_u32_e32 vcc, 2.0, v146
	s_nop 1
	v_cndmask_b32_e32 v49, v246, v49, vcc
